# grid barrier: all waiters (non-leader WGs and non-last XCD leaders) poll the cross-XCC arrival counter against (gen+1)*nXCC instead of the release generation words
# speedup vs baseline: 1.0065x; 1.0011x over previous
.LBB0_127:
	s_or_b64 exec, exec, s[20:21]
	v_cvt_f32_u32_e32 v5, v3
	s_waitcnt vmcnt(0)
	v_readfirstlane_b32 s3, v4
	v_sub_u32_e32 v4, 0, v3
	v_rcp_iflag_f32_e32 v5, v5
	v_add_u32_e32 v6, s3, v2
	v_mul_f32_e32 v5, 0x4f7ffffe, v5
	v_cvt_u32_f32_e32 v5, v5
	v_mul_lo_u32 v2, v4, v5
	v_mul_hi_u32 v2, v5, v2
	v_add_u32_e32 v2, v5, v2
	v_mul_hi_u32 v2, v6, v2
	v_mul_lo_u32 v4, v2, v3
	v_sub_u32_e32 v4, v6, v4
	v_add_u32_e32 v5, 1, v2
	v_cmp_ge_u32_e32 vcc, v4, v3
	s_nop 1
	v_cndmask_b32_e32 v2, v2, v5, vcc
	v_sub_u32_e32 v5, v4, v3
	v_cndmask_b32_e32 v4, v4, v5, vcc
	v_add_u32_e32 v5, 1, v2
	v_cmp_ge_u32_e32 vcc, v4, v3
	v_add_u32_e32 v4, 1, v6
	s_nop 0
	v_cndmask_b32_e32 v2, v2, v5, vcc
	v_mul_lo_u32 v5, v3, v2
	v_add_u32_e32 v3, v5, v3
	v_cmp_ne_u32_e32 vcc, v4, v3
	s_and_saveexec_b64 s[4:5], vcc
	s_xor_b64 s[20:21], exec, s[4:5]
	s_cbranch_execz .LBB0_141
	s_waitcnt lgkmcnt(0)
	v_mad_u32_u24 v2, v2, v1, v1
	v_mov_b32_e32 v1, 0
	global_load_dword v3, v1, s[92:93] offset:-256 sc1
	s_waitcnt vmcnt(0)
	v_cmp_gt_u32_e32 vcc, v2, v3
	s_and_saveexec_b64 s[22:23], vcc
	s_cbranch_execz .LBB0_140
	s_mov_b32 s3, 1
	s_mov_b64 s[24:25], 0
	s_branch .LBB0_131

.LBB0_133:
	global_load_dword v3, v1, s[92:93] offset:-256 sc1
	s_add_i32 s3, s3, 1
	s_mov_b64 s[30:31], -1
	s_waitcnt vmcnt(0)
	v_cmp_le_u32_e32 vcc, v2, v3
	s_orn2_b64 s[28:29], vcc, exec
	s_branch .LBB0_130

.LBB0_144:
	s_or_b64 exec, exec, s[22:23]
	v_cvt_f32_u32_e32 v4, v1
	s_waitcnt vmcnt(0)
	v_readfirstlane_b32 s3, v3
	s_mov_b64 s[22:23], -1
	v_rcp_iflag_f32_e32 v4, v4
	v_add_u32_e32 v2, s3, v2
	v_add_u32_e32 v5, 1, v2
	v_mul_f32_e32 v3, 0x4f7ffffe, v4
	v_cvt_u32_f32_e32 v3, v3
	v_sub_u32_e32 v4, 0, v1
	v_mul_lo_u32 v4, v4, v3
	v_mul_hi_u32 v4, v3, v4
	v_add_u32_e32 v3, v3, v4
	v_mul_hi_u32 v3, v2, v3
	v_mul_lo_u32 v4, v3, v1
	v_sub_u32_e32 v2, v2, v4
	v_add_u32_e32 v6, 1, v3
	v_cmp_ge_u32_e32 vcc, v2, v1
	v_sub_u32_e32 v4, v2, v1
	s_nop 0
	v_cndmask_b32_e32 v3, v3, v6, vcc
	v_cndmask_b32_e32 v2, v2, v4, vcc
	v_add_u32_e32 v4, 1, v3
	v_cmp_ge_u32_e32 vcc, v2, v1
	s_nop 1
	v_cndmask_b32_e32 v4, v3, v4, vcc
	v_mul_lo_u32 v2, v1, v4
	v_add_u32_e32 v1, v2, v1
	v_cmp_ne_u32_e32 vcc, v5, v1
	v_mov_b32_e32 v4, v1
	v_mov_b64_e32 v[2:3], s[92:93]
	s_and_saveexec_b64 s[20:21], vcc
	s_cbranch_execz .LBB0_156
	v_mov_b32_e32 v1, 0
	global_load_dword v2, v1, s[92:93] offset:-256 sc1
	s_mov_b64 s[24:25], 0
	s_waitcnt vmcnt(0)
	v_cmp_gt_u32_e32 vcc, v4, v2
	s_and_saveexec_b64 s[22:23], vcc
	s_cbranch_execz .LBB0_155
	s_mov_b32 s3, 1
	s_branch .LBB0_148

.LBB0_150:
	global_load_dword v2, v1, s[92:93] offset:-256 sc1
	s_add_i32 s3, s3, 1
	s_mov_b64 s[28:29], -1
	s_waitcnt vmcnt(0)
	v_cmp_le_u32_e32 vcc, v4, v2
	s_orn2_b64 s[34:35], vcc, exec
	s_branch .LBB0_147

.LBB0_344:
	s_or_b64 exec, exec, s[20:21]
	v_cvt_f32_u32_e32 v5, v3
	s_waitcnt vmcnt(0)
	v_readfirstlane_b32 s4, v4
	v_sub_u32_e32 v4, 0, v3
	v_rcp_iflag_f32_e32 v5, v5
	v_add_u32_e32 v6, s4, v2
	v_mul_f32_e32 v5, 0x4f7ffffe, v5
	v_cvt_u32_f32_e32 v5, v5
	v_mul_lo_u32 v2, v4, v5
	v_mul_hi_u32 v2, v5, v2
	v_add_u32_e32 v2, v5, v2
	v_mul_hi_u32 v2, v6, v2
	v_mul_lo_u32 v4, v2, v3
	v_sub_u32_e32 v4, v6, v4
	v_add_u32_e32 v5, 1, v2
	v_cmp_ge_u32_e32 vcc, v4, v3
	s_nop 1
	v_cndmask_b32_e32 v2, v2, v5, vcc
	v_sub_u32_e32 v5, v4, v3
	v_cndmask_b32_e32 v4, v4, v5, vcc
	v_add_u32_e32 v5, 1, v2
	v_cmp_ge_u32_e32 vcc, v4, v3
	v_add_u32_e32 v4, 1, v6
	s_nop 0
	v_cndmask_b32_e32 v2, v2, v5, vcc
	v_mul_lo_u32 v5, v3, v2
	v_add_u32_e32 v3, v5, v3
	v_cmp_ne_u32_e32 vcc, v4, v3
	s_and_saveexec_b64 s[4:5], vcc
	s_xor_b64 s[20:21], exec, s[4:5]
	s_cbranch_execz .LBB0_358
	s_waitcnt lgkmcnt(0)
	v_mad_u32_u24 v2, v2, v1, v1
	v_mov_b32_e32 v1, 0
	global_load_dword v3, v1, s[92:93] offset:-256 sc1
	s_waitcnt vmcnt(0)
	v_cmp_gt_u32_e32 vcc, v2, v3
	s_and_saveexec_b64 s[22:23], vcc
	s_cbranch_execz .LBB0_357
	s_mov_b32 s4, 1
	s_mov_b64 s[24:25], 0
	s_branch .LBB0_348

.LBB0_350:
	global_load_dword v3, v1, s[92:93] offset:-256 sc1
	s_add_i32 s4, s4, 1
	s_mov_b64 s[30:31], -1
	s_waitcnt vmcnt(0)
	v_cmp_le_u32_e32 vcc, v2, v3
	s_orn2_b64 s[28:29], vcc, exec
	s_branch .LBB0_347

.LBB0_361:
	s_or_b64 exec, exec, s[22:23]
	v_cvt_f32_u32_e32 v4, v1
	s_waitcnt vmcnt(0)
	v_readfirstlane_b32 s4, v3
	s_mov_b64 s[22:23], -1
	v_rcp_iflag_f32_e32 v4, v4
	v_add_u32_e32 v2, s4, v2
	v_add_u32_e32 v5, 1, v2
	v_mul_f32_e32 v3, 0x4f7ffffe, v4
	v_cvt_u32_f32_e32 v3, v3
	v_sub_u32_e32 v4, 0, v1
	v_mul_lo_u32 v4, v4, v3
	v_mul_hi_u32 v4, v3, v4
	v_add_u32_e32 v3, v3, v4
	v_mul_hi_u32 v3, v2, v3
	v_mul_lo_u32 v4, v3, v1
	v_sub_u32_e32 v2, v2, v4
	v_add_u32_e32 v6, 1, v3
	v_cmp_ge_u32_e32 vcc, v2, v1
	v_sub_u32_e32 v4, v2, v1
	s_nop 0
	v_cndmask_b32_e32 v3, v3, v6, vcc
	v_cndmask_b32_e32 v2, v2, v4, vcc
	v_add_u32_e32 v4, 1, v3
	v_cmp_ge_u32_e32 vcc, v2, v1
	s_nop 1
	v_cndmask_b32_e32 v4, v3, v4, vcc
	v_mul_lo_u32 v2, v1, v4
	v_add_u32_e32 v1, v2, v1
	v_cmp_ne_u32_e32 vcc, v5, v1
	v_mov_b32_e32 v4, v1
	v_mov_b64_e32 v[2:3], s[92:93]
	s_and_saveexec_b64 s[20:21], vcc
	s_cbranch_execz .LBB0_373
	v_mov_b32_e32 v1, 0
	global_load_dword v2, v1, s[92:93] offset:-256 sc1
	s_mov_b64 s[24:25], 0
	s_waitcnt vmcnt(0)
	v_cmp_gt_u32_e32 vcc, v4, v2
	s_and_saveexec_b64 s[22:23], vcc
	s_cbranch_execz .LBB0_372
	s_mov_b32 s4, 1
	s_branch .LBB0_365

.LBB0_367:
	global_load_dword v2, v1, s[92:93] offset:-256 sc1
	s_add_i32 s4, s4, 1
	s_mov_b64 s[28:29], -1
	s_waitcnt vmcnt(0)
	v_cmp_le_u32_e32 vcc, v4, v2
	s_orn2_b64 s[34:35], vcc, exec
	s_branch .LBB0_364

.LBB0_614:
	s_or_b64 exec, exec, s[20:21]
	v_cvt_f32_u32_e32 v6, v4
	s_waitcnt vmcnt(0)
	v_readfirstlane_b32 s4, v5
	v_sub_u32_e32 v5, 0, v4
	v_rcp_iflag_f32_e32 v6, v6
	v_add_u32_e32 v7, s4, v3
	v_mul_f32_e32 v6, 0x4f7ffffe, v6
	v_cvt_u32_f32_e32 v6, v6
	v_mul_lo_u32 v3, v5, v6
	v_mul_hi_u32 v3, v6, v3
	v_add_u32_e32 v3, v6, v3
	v_mul_hi_u32 v3, v7, v3
	v_mul_lo_u32 v5, v3, v4
	v_sub_u32_e32 v5, v7, v5
	v_add_u32_e32 v6, 1, v3
	v_cmp_ge_u32_e32 vcc, v5, v4
	s_nop 1
	v_cndmask_b32_e32 v3, v3, v6, vcc
	v_sub_u32_e32 v6, v5, v4
	v_cndmask_b32_e32 v5, v5, v6, vcc
	v_add_u32_e32 v6, 1, v3
	v_cmp_ge_u32_e32 vcc, v5, v4
	v_add_u32_e32 v5, 1, v7
	s_nop 0
	v_cndmask_b32_e32 v3, v3, v6, vcc
	v_mul_lo_u32 v6, v4, v3
	v_add_u32_e32 v4, v6, v4
	v_cmp_ne_u32_e32 vcc, v5, v4
	s_and_saveexec_b64 s[4:5], vcc
	s_xor_b64 s[20:21], exec, s[4:5]
	s_cbranch_execz .LBB0_628
	s_waitcnt lgkmcnt(0)
	v_mad_u32_u24 v3, v3, v2, v2
	v_mov_b32_e32 v2, 0
	global_load_dword v4, v2, s[92:93] offset:-256 sc1
	s_waitcnt vmcnt(0)
	v_cmp_gt_u32_e32 vcc, v3, v4
	s_and_saveexec_b64 s[22:23], vcc
	s_cbranch_execz .LBB0_627
	s_mov_b32 s4, 1
	s_mov_b64 s[24:25], 0
	s_branch .LBB0_618

.LBB0_620:
	global_load_dword v4, v2, s[92:93] offset:-256 sc1
	s_add_i32 s4, s4, 1
	s_mov_b64 s[30:31], -1
	s_waitcnt vmcnt(0)
	v_cmp_le_u32_e32 vcc, v3, v4
	s_orn2_b64 s[28:29], vcc, exec
	s_branch .LBB0_617

.LBB0_631:
	s_or_b64 exec, exec, s[22:23]
	s_waitcnt vmcnt(0)
	v_readfirstlane_b32 s4, v4
	v_cvt_f32_u32_e32 v4, v2
	v_sub_u32_e32 v5, 0, v2
	v_add_u32_e32 v3, s4, v3
	s_mov_b64 s[22:23], -1
	v_rcp_iflag_f32_e32 v4, v4
	s_nop 0
	v_mul_f32_e32 v4, 0x4f7ffffe, v4
	v_cvt_u32_f32_e32 v4, v4
	v_mul_lo_u32 v5, v5, v4
	v_mul_hi_u32 v5, v4, v5
	v_add_u32_e32 v4, v4, v5
	v_mul_hi_u32 v4, v3, v4
	v_mul_lo_u32 v5, v4, v2
	v_sub_u32_e32 v5, v3, v5
	v_cmp_ge_u32_e32 vcc, v5, v2
	v_add_u32_e32 v6, 1, v4
	v_add_u32_e32 v3, 1, v3
	v_cndmask_b32_e32 v4, v4, v6, vcc
	v_sub_u32_e32 v6, v5, v2
	v_cndmask_b32_e32 v5, v5, v6, vcc
	v_cmp_ge_u32_e32 vcc, v5, v2
	v_add_u32_e32 v5, 1, v4
	s_nop 0
	v_cndmask_b32_e32 v4, v4, v5, vcc
	v_mul_lo_u32 v5, v2, v4
	v_add_u32_e32 v2, v5, v2
	v_cmp_ne_u32_e32 vcc, v3, v2
	v_mov_b32_e32 v4, v2
	v_mov_b64_e32 v[2:3], s[92:93]
	s_and_saveexec_b64 s[20:21], vcc
	s_cbranch_execz .LBB0_643
	v_mov_b32_e32 v2, 0
	global_load_dword v3, v2, s[92:93] offset:-256 sc1
	s_mov_b64 s[24:25], 0
	s_waitcnt vmcnt(0)
	v_cmp_gt_u32_e32 vcc, v4, v3
	s_and_saveexec_b64 s[22:23], vcc
	s_cbranch_execz .LBB0_642
	s_mov_b32 s4, 1
	s_branch .LBB0_635

.LBB0_637:
	global_load_dword v3, v2, s[92:93] offset:-256 sc1
	s_add_i32 s4, s4, 1
	s_mov_b64 s[28:29], -1
	s_waitcnt vmcnt(0)
	v_cmp_le_u32_e32 vcc, v4, v3
	s_orn2_b64 s[34:35], vcc, exec
	s_branch .LBB0_634

.LBB0_1559:
	s_or_b64 exec, exec, s[18:19]
	v_cvt_f32_u32_e32 v6, v4
	s_waitcnt vmcnt(0)
	v_readfirstlane_b32 s4, v5
	v_sub_u32_e32 v5, 0, v4
	v_rcp_iflag_f32_e32 v6, v6
	v_add_u32_e32 v7, s4, v3
	v_mul_f32_e32 v6, 0x4f7ffffe, v6
	v_cvt_u32_f32_e32 v6, v6
	v_mul_lo_u32 v3, v5, v6
	v_mul_hi_u32 v3, v6, v3
	v_add_u32_e32 v3, v6, v3
	v_mul_hi_u32 v3, v7, v3
	v_mul_lo_u32 v5, v3, v4
	v_sub_u32_e32 v5, v7, v5
	v_add_u32_e32 v6, 1, v3
	v_cmp_ge_u32_e32 vcc, v5, v4
	s_nop 1
	v_cndmask_b32_e32 v3, v3, v6, vcc
	v_sub_u32_e32 v6, v5, v4
	v_cndmask_b32_e32 v5, v5, v6, vcc
	v_add_u32_e32 v6, 1, v3
	v_cmp_ge_u32_e32 vcc, v5, v4
	v_add_u32_e32 v5, 1, v7
	s_nop 0
	v_cndmask_b32_e32 v3, v3, v6, vcc
	v_mul_lo_u32 v6, v4, v3
	v_add_u32_e32 v4, v6, v4
	v_cmp_ne_u32_e32 vcc, v5, v4
	s_and_saveexec_b64 s[4:5], vcc
	s_xor_b64 s[18:19], exec, s[4:5]
	s_cbranch_execz .LBB0_1573
	s_waitcnt lgkmcnt(0)
	v_mad_u32_u24 v3, v3, v2, v2
	v_mov_b32_e32 v2, 0
	global_load_dword v4, v2, s[92:93] offset:-256 sc1
	s_waitcnt vmcnt(0)
	v_cmp_gt_u32_e32 vcc, v3, v4
	s_and_saveexec_b64 s[20:21], vcc
	s_cbranch_execz .LBB0_1572
	s_mov_b32 s4, 1
	s_mov_b64 s[22:23], 0
	s_branch .LBB0_1563

.LBB0_1565:
	global_load_dword v4, v2, s[92:93] offset:-256 sc1
	s_add_i32 s4, s4, 1
	s_mov_b64 s[28:29], -1
	s_waitcnt vmcnt(0)
	v_cmp_le_u32_e32 vcc, v3, v4
	s_orn2_b64 s[26:27], vcc, exec
	s_branch .LBB0_1562

.LBB0_1576:
	s_or_b64 exec, exec, s[20:21]
	s_waitcnt vmcnt(0)
	v_readfirstlane_b32 s4, v4
	v_cvt_f32_u32_e32 v4, v2
	v_sub_u32_e32 v5, 0, v2
	v_add_u32_e32 v3, s4, v3
	s_mov_b64 s[20:21], -1
	v_rcp_iflag_f32_e32 v4, v4
	s_nop 0
	v_mul_f32_e32 v4, 0x4f7ffffe, v4
	v_cvt_u32_f32_e32 v4, v4
	v_mul_lo_u32 v5, v5, v4
	v_mul_hi_u32 v5, v4, v5
	v_add_u32_e32 v4, v4, v5
	v_mul_hi_u32 v4, v3, v4
	v_mul_lo_u32 v5, v4, v2
	v_sub_u32_e32 v5, v3, v5
	v_cmp_ge_u32_e32 vcc, v5, v2
	v_add_u32_e32 v6, 1, v4
	v_add_u32_e32 v3, 1, v3
	v_cndmask_b32_e32 v4, v4, v6, vcc
	v_sub_u32_e32 v6, v5, v2
	v_cndmask_b32_e32 v5, v5, v6, vcc
	v_cmp_ge_u32_e32 vcc, v5, v2
	v_add_u32_e32 v5, 1, v4
	s_nop 0
	v_cndmask_b32_e32 v4, v4, v5, vcc
	v_mul_lo_u32 v5, v2, v4
	v_add_u32_e32 v2, v5, v2
	v_cmp_ne_u32_e32 vcc, v3, v2
	v_mov_b32_e32 v4, v2
	v_mov_b64_e32 v[2:3], s[92:93]
	s_and_saveexec_b64 s[18:19], vcc
	s_cbranch_execz .LBB0_1588
	v_mov_b32_e32 v2, 0
	global_load_dword v3, v2, s[92:93] offset:-256 sc1
	s_mov_b64 s[22:23], 0
	s_waitcnt vmcnt(0)
	v_cmp_gt_u32_e32 vcc, v4, v3
	s_and_saveexec_b64 s[20:21], vcc
	s_cbranch_execz .LBB0_1587
	s_mov_b32 s4, 1
	s_branch .LBB0_1580

.LBB0_1582:
	global_load_dword v3, v2, s[92:93] offset:-256 sc1
	s_add_i32 s4, s4, 1
	s_mov_b64 s[26:27], -1
	s_waitcnt vmcnt(0)
	v_cmp_le_u32_e32 vcc, v4, v3
	s_orn2_b64 s[30:31], vcc, exec
	s_branch .LBB0_1579

.LBB0_1646:
	s_or_b64 exec, exec, s[4:5]
	v_cvt_f32_u32_e32 v5, v3
	s_waitcnt vmcnt(0)
	v_readfirstlane_b32 s4, v4
	v_sub_u32_e32 v4, 0, v3
	v_rcp_iflag_f32_e32 v5, v5
	v_add_u32_e32 v6, s4, v2
	v_mul_f32_e32 v5, 0x4f7ffffe, v5
	v_cvt_u32_f32_e32 v5, v5
	v_mul_lo_u32 v2, v4, v5
	v_mul_hi_u32 v2, v5, v2
	v_add_u32_e32 v2, v5, v2
	v_mul_hi_u32 v2, v6, v2
	v_mul_lo_u32 v4, v2, v3
	v_sub_u32_e32 v4, v6, v4
	v_add_u32_e32 v5, 1, v2
	v_cmp_ge_u32_e32 vcc, v4, v3
	s_nop 1
	v_cndmask_b32_e32 v2, v2, v5, vcc
	v_sub_u32_e32 v5, v4, v3
	v_cndmask_b32_e32 v4, v4, v5, vcc
	v_add_u32_e32 v5, 1, v2
	v_cmp_ge_u32_e32 vcc, v4, v3
	v_add_u32_e32 v4, 1, v6
	s_nop 0
	v_cndmask_b32_e32 v2, v2, v5, vcc
	v_mul_lo_u32 v5, v3, v2
	v_add_u32_e32 v3, v5, v3
	v_cmp_ne_u32_e32 vcc, v4, v3
	s_and_saveexec_b64 s[4:5], vcc
	s_xor_b64 s[4:5], exec, s[4:5]
	s_cbranch_execz .LBB0_1660
	s_waitcnt lgkmcnt(0)
	v_mad_u32_u24 v2, v2, v1, v1
	v_mov_b32_e32 v1, 0
	global_load_dword v3, v1, s[92:93] offset:-256 sc1
	s_waitcnt vmcnt(0)
	v_cmp_gt_u32_e32 vcc, v2, v3
	s_and_saveexec_b64 s[6:7], vcc
	s_cbranch_execz .LBB0_1659
	s_mov_b32 s18, 1
	s_mov_b64 s[8:9], 0
	s_branch .LBB0_1650

.LBB0_1652:
	global_load_dword v3, v1, s[92:93] offset:-256 sc1
	s_add_i32 s18, s18, 1
	s_mov_b64 s[14:15], -1
	s_waitcnt vmcnt(0)
	v_cmp_le_u32_e32 vcc, v2, v3
	s_orn2_b64 s[12:13], vcc, exec
	s_branch .LBB0_1649

.LBB0_1663:
	s_or_b64 exec, exec, s[6:7]
	v_cvt_f32_u32_e32 v4, v1
	s_waitcnt vmcnt(0)
	v_readfirstlane_b32 s4, v3
	s_mov_b64 s[6:7], -1
	v_rcp_iflag_f32_e32 v4, v4
	v_add_u32_e32 v2, s4, v2
	v_add_u32_e32 v5, 1, v2
	v_mul_f32_e32 v3, 0x4f7ffffe, v4
	v_cvt_u32_f32_e32 v3, v3
	v_sub_u32_e32 v4, 0, v1
	v_mul_lo_u32 v4, v4, v3
	v_mul_hi_u32 v4, v3, v4
	v_add_u32_e32 v3, v3, v4
	v_mul_hi_u32 v3, v2, v3
	v_mul_lo_u32 v4, v3, v1
	v_sub_u32_e32 v2, v2, v4
	v_add_u32_e32 v6, 1, v3
	v_cmp_ge_u32_e32 vcc, v2, v1
	v_sub_u32_e32 v4, v2, v1
	s_nop 0
	v_cndmask_b32_e32 v3, v3, v6, vcc
	v_cndmask_b32_e32 v2, v2, v4, vcc
	v_add_u32_e32 v4, 1, v3
	v_cmp_ge_u32_e32 vcc, v2, v1
	s_nop 1
	v_cndmask_b32_e32 v4, v3, v4, vcc
	v_mul_lo_u32 v2, v1, v4
	v_add_u32_e32 v1, v2, v1
	v_cmp_ne_u32_e32 vcc, v5, v1
	v_mov_b32_e32 v4, v1
	v_mov_b64_e32 v[2:3], s[92:93]
	s_and_saveexec_b64 s[4:5], vcc
	s_cbranch_execz .LBB0_1675
	v_mov_b32_e32 v1, 0
	global_load_dword v2, v1, s[92:93] offset:-256 sc1
	s_mov_b64 s[8:9], 0
	s_waitcnt vmcnt(0)
	v_cmp_gt_u32_e32 vcc, v4, v2
	s_and_saveexec_b64 s[6:7], vcc
	s_cbranch_execz .LBB0_1674
	s_mov_b32 s18, 1
	s_branch .LBB0_1667

.LBB0_1669:
	global_load_dword v2, v1, s[92:93] offset:-256 sc1
	s_add_i32 s18, s18, 1
	s_mov_b64 s[12:13], -1
	s_waitcnt vmcnt(0)
	v_cmp_le_u32_e32 vcc, v4, v2
	s_orn2_b64 s[16:17], vcc, exec
	s_branch .LBB0_1666
